# ATTN QK: second K-tile batch gathers hoisted ahead of first batch compute (software prefetch), on top of v53
# baseline (speedup 1.0000x reference)
; DI void attn_item(const P& p, int b, int kvh, int quad4, char* smem, const AttnPre& pre) {
;     ...
;   const unsigned char* kb = p.k8 + ((size_t)b * SEQ) * 256 + kvh * 128 + quad * 16;
;   int myidx[16];
; #pragma unroll
;   for (int kt = 0; kt < 16; ++kt) myidx[kt] = idx[kt * 16 + r];
; #pragma unroll
;   for (int kt0 = 0; kt0 < 16; kt0 += 8) {
;     u32x4 kraw[8][2];
; #pragma unroll
;     for (int u = 0; u < 8; ++u) {
;       const unsigned char* kp = kb + (size_t)myidx[kt0 + u] * 256;
;       kraw[u][0] = *(const u32x4*)kp; kraw[u][1] = *(const u32x4*)(kp + 64);
;     }
.LBB0_313:
	s_or_b64 exec, exec, s[4:5]
	v_and_b32_e32 v105, 15, v35
	v_lshl_add_u32 v108, v105, 2, v34
	v_add_u32_e32 v109, 0x1000, v108
	v_and_b32_e32 v192, 48, v35
	s_waitcnt vmcnt(4)
	ds_read2_b32 v[32:33], v109 offset1:16
	ds_read2_b32 v[34:35], v109 offset0:32 offset1:48
	s_ashr_i32 s9, s6, 11
	ds_read2_b32 v[40:41], v109 offset0:64 offset1:80
	s_lshl_b32 s10, s9, 7
	s_waitcnt vmcnt(4) lgkmcnt(2)
	v_ashrrev_i32_e32 v37, 31, v32
	v_mov_b32_e32 v36, v32
	v_ashrrev_i32_e32 v39, 31, v33
	v_mov_b32_e32 v38, v33
	s_waitcnt lgkmcnt(1)
	v_ashrrev_i32_e32 v33, 31, v34
	v_mov_b32_e32 v32, v34
	v_ashrrev_i32_e32 v43, 31, v35
	v_mov_b32_e32 v42, v35
	ds_read2_b32 v[34:35], v109 offset0:96 offset1:112
	s_ashr_i32 s11, s10, 31
	v_readlane_b32 s4, v250, 13
	s_add_u32 s4, s4, s10
	v_readlane_b32 s5, v250, 14
	s_addc_u32 s5, s5, s11
	s_waitcnt lgkmcnt(1)
	v_ashrrev_i32_e32 v45, 31, v40
	v_mov_b32_e32 v44, v40
	v_ashrrev_i32_e32 v47, 31, v41
	v_mov_b32_e32 v46, v41
	s_waitcnt lgkmcnt(0)
	ds_read2_b32 v[228:229], v109 offset0:128 offset1:144
	ds_read2_b32 v[230:231], v109 offset0:160 offset1:176
	ds_read2_b32 v[232:233], v109 offset0:192 offset1:208
	ds_read2_b32 v[234:235], v109 offset0:224 offset1:240
	v_ashrrev_i32_e32 v41, 31, v34
	v_mov_b32_e32 v40, v34
	v_ashrrev_i32_e32 v93, 31, v35
	v_mov_b32_e32 v92, v35
	v_lshl_add_u64 v[100:101], s[4:5], 0, v[192:193]
	v_lshlrev_b64 v[34:35], 8, v[36:37]
	v_lshl_add_u64 v[34:35], v[100:101], 0, v[34:35]
	global_load_dwordx4 v[110:113], v[34:35], off
	global_load_dwordx4 v[114:117], v[34:35], off offset:64
	v_lshlrev_b64 v[34:35], 8, v[38:39]
	v_lshlrev_b64 v[32:33], 8, v[32:33]
	v_lshl_add_u64 v[34:35], v[100:101], 0, v[34:35]
	v_lshl_add_u64 v[32:33], v[100:101], 0, v[32:33]
	global_load_dwordx4 v[84:87], v[34:35], off
	global_load_dwordx4 v[80:83], v[34:35], off offset:64
	global_load_dwordx4 v[76:79], v[32:33], off
	global_load_dwordx4 v[72:75], v[32:33], off offset:64
	v_lshlrev_b64 v[32:33], 8, v[42:43]
	v_lshl_add_u64 v[32:33], v[100:101], 0, v[32:33]
	global_load_dwordx4 v[68:71], v[32:33], off
	global_load_dwordx4 v[64:67], v[32:33], off offset:64
	v_lshlrev_b64 v[32:33], 8, v[44:45]
	v_lshl_add_u64 v[32:33], v[100:101], 0, v[32:33]
	global_load_dwordx4 v[60:63], v[32:33], off
	global_load_dwordx4 v[56:59], v[32:33], off offset:64
	v_lshlrev_b64 v[32:33], 8, v[46:47]
	v_lshl_add_u64 v[32:33], v[100:101], 0, v[32:33]
	global_load_dwordx4 v[52:55], v[32:33], off
	global_load_dwordx4 v[48:51], v[32:33], off offset:64
	v_lshlrev_b64 v[32:33], 8, v[40:41]
	v_lshl_add_u64 v[32:33], v[100:101], 0, v[32:33]
	global_load_dwordx4 v[44:47], v[32:33], off
	global_load_dwordx4 v[40:43], v[32:33], off offset:64
	v_lshlrev_b64 v[32:33], 8, v[92:93]
	v_lshl_add_u64 v[32:33], v[100:101], 0, v[32:33]
	global_load_dwordx4 v[36:39], v[32:33], off
	s_nop 0
	global_load_dwordx4 v[32:35], v[32:33], off offset:64
	s_waitcnt lgkmcnt(0)
	v_ashrrev_i32_e32 v213, 31, v228
	v_mov_b32_e32 v212, v228
	v_lshlrev_b64 v[212:213], 8, v[212:213]
	v_lshl_add_u64 v[212:213], v[100:101], 0, v[212:213]
	global_load_dwordx4 v[120:123], v[212:213], off
	global_load_dwordx4 v[124:127], v[212:213], off offset:64
	s_nop 0
	v_ashrrev_i32_e32 v213, 31, v229
	v_mov_b32_e32 v212, v229
	v_lshlrev_b64 v[212:213], 8, v[212:213]
	v_lshl_add_u64 v[212:213], v[100:101], 0, v[212:213]
	global_load_dwordx4 v[128:131], v[212:213], off
	global_load_dwordx4 v[132:135], v[212:213], off offset:64
	s_nop 0
	v_ashrrev_i32_e32 v213, 31, v230
	v_mov_b32_e32 v212, v230
	v_lshlrev_b64 v[212:213], 8, v[212:213]
	v_lshl_add_u64 v[212:213], v[100:101], 0, v[212:213]
	global_load_dwordx4 v[136:139], v[212:213], off
	global_load_dwordx4 v[140:143], v[212:213], off offset:64
	s_nop 0
	v_ashrrev_i32_e32 v213, 31, v231
	v_mov_b32_e32 v212, v231
	v_lshlrev_b64 v[212:213], 8, v[212:213]
	v_lshl_add_u64 v[212:213], v[100:101], 0, v[212:213]
	global_load_dwordx4 v[144:147], v[212:213], off
	global_load_dwordx4 v[148:151], v[212:213], off offset:64
	s_nop 0
	v_ashrrev_i32_e32 v213, 31, v232
	v_mov_b32_e32 v212, v232
	v_lshlrev_b64 v[212:213], 8, v[212:213]
	v_lshl_add_u64 v[212:213], v[100:101], 0, v[212:213]
	global_load_dwordx4 v[152:155], v[212:213], off
	global_load_dwordx4 v[156:159], v[212:213], off offset:64
	s_nop 0
	v_ashrrev_i32_e32 v213, 31, v233
	v_mov_b32_e32 v212, v233
	v_lshlrev_b64 v[212:213], 8, v[212:213]
	v_lshl_add_u64 v[212:213], v[100:101], 0, v[212:213]
	global_load_dwordx4 v[160:163], v[212:213], off
	global_load_dwordx4 v[164:167], v[212:213], off offset:64
	s_nop 0
	v_ashrrev_i32_e32 v213, 31, v234
	v_mov_b32_e32 v212, v234
	v_lshlrev_b64 v[212:213], 8, v[212:213]
	v_lshl_add_u64 v[212:213], v[100:101], 0, v[212:213]
	global_load_dwordx4 v[196:199], v[212:213], off
	global_load_dwordx4 v[200:203], v[212:213], off offset:64
	s_nop 0
	v_ashrrev_i32_e32 v213, 31, v235
	v_mov_b32_e32 v212, v235
	v_lshlrev_b64 v[212:213], 8, v[212:213]
	v_lshl_add_u64 v[212:213], v[100:101], 0, v[212:213]
	global_load_dwordx4 v[204:207], v[212:213], off
	global_load_dwordx4 v[208:211], v[212:213], off offset:64
	s_nop 0
	s_waitcnt vmcnt(34)
	v_lshlrev_b32_e32 v92, 16, v28
	v_and_b32_e32 v28, 0xffff0000, v28
	v_mov_b32_e32 v95, v193
	v_lshlrev_b32_e32 v94, 16, v30
	v_and_b32_e32 v30, 0xffff0000, v30
	v_cvt_pk_fp8_f32 v95, v92, v28
	v_mov_b32_e32 v28, v193
	v_cvt_pk_fp8_f32 v28, v94, v30
	v_lshlrev_b32_e32 v93, 16, v29
	v_and_b32_e32 v29, 0xffff0000, v29
	v_lshlrev_b32_e32 v30, 16, v31
	v_and_b32_e32 v31, 0xffff0000, v31
	v_cvt_pk_fp8_f32 v95, v93, v29 op_sel:[0,0,1]
	v_lshlrev_b32_e32 v29, 16, v24
	v_and_b32_e32 v24, 0xffff0000, v24
	v_mov_b32_e32 v94, v193
	v_cvt_pk_fp8_f32 v28, v30, v31 op_sel:[0,0,1]
	v_lshlrev_b32_e32 v31, 16, v26
	v_and_b32_e32 v26, 0xffff0000, v26
	v_cvt_pk_fp8_f32 v94, v29, v24
	v_mov_b32_e32 v24, v193
	v_cvt_pk_fp8_f32 v24, v31, v26
	v_lshlrev_b32_e32 v26, 16, v27
	v_and_b32_e32 v27, 0xffff0000, v27
	v_lshlrev_b32_e32 v30, 16, v25
	v_cvt_pk_fp8_f32 v24, v26, v27 op_sel:[0,0,1]
	v_and_b32_e32 v25, 0xffff0000, v25
	v_cvt_pk_fp8_f32 v94, v30, v25 op_sel:[0,0,1]
	v_cmp_lt_u32_e32 vcc, 3, v105
	s_waitcnt vmcnt(32)
; DI void attn_item(const P& p, int b, int kvh, int quad4, char* smem, const AttnPre& pre) {
;     ...
;       for (int e = 0; e < 4; ++e) { f[2 * e] = __uint_as_float(tq[e] << 16); f[2 * e + 1] = __uint_as_float(tq[e] & 0xffff0000u); }
;       const uint2 pk = pack8_fp8(f);
;       long v = (long)(((unsigned long long)pk.y << 32) | (unsigned long long)pk.x);
;       if (r >= 4) v = 0;
;       qa8[s] = v;
;     }
;   }
;   __builtin_amdgcn_wave_barrier();
;   const unsigned char* kb = p.k8 + ((size_t)b * SEQ) * 256 + kvh * 128 + quad * 16;
;   int myidx[16];
; #pragma unroll
;   for (int kt = 0; kt < 16; ++kt) myidx[kt] = idx[kt * 16 + r];
; #pragma unroll
;   for (int kt0 = 0; kt0 < 16; kt0 += 8) {
;     u32x4 kraw[8][2];
; #pragma unroll
;     for (int u = 0; u < 8; ++u) {
;       const unsigned char* kp = kb + (size_t)myidx[kt0 + u] * 256;
;       kraw[u][0] = *(const u32x4*)kp; kraw[u][1] = *(const u32x4*)(kp + 64);
;     }
; #pragma unroll
;     for (int u = 0; u < 8; ++u) {
;       const int n = (kt0 + u) * 16 + r;
;       f32x4 acc = {0.f, 0.f, 0.f, 0.f};
; #pragma unroll
;       for (int S = 0; S < 2; ++S) {
;         const long k0 = (long)(((unsigned long long)kraw[u][S][1] << 32) | (unsigned long long)kraw[u][S][0]);
;         const long k1 = (long)(((unsigned long long)kraw[u][S][3] << 32) | (unsigned long long)kraw[u][S][2]);
;         acc = __builtin_amdgcn_mfma_f32_16x16x32_fp8_fp8(qa8[2 * S], k0, acc, 0, 0, 0);
;         acc = __builtin_amdgcn_mfma_f32_16x16x32_fp8_fp8(qa8[2 * S + 1], k1, acc, 0, 0, 0);
;       }
;       if (quad == 0) {
;         const bool ok = n < cnt;
; #pragma unroll
;         for (int h = 0; h < 4; ++h) L[h * 256 + n] = ok ? acc[h] * ATT_SCALE : -INFINITY;
;       }
	v_lshlrev_b32_e32 v25, 16, v22
	v_and_b32_e32 v22, 0xffff0000, v22
	v_mov_b32_e32 v27, v193
	v_cndmask_b32_e64 v92, v95, 0, vcc
	v_cndmask_b32_e64 v95, v24, 0, vcc
	v_lshlrev_b32_e32 v24, 16, v20
	v_and_b32_e32 v20, 0xffff0000, v20
	v_lshlrev_b32_e32 v26, 16, v23
	v_cvt_pk_fp8_f32 v27, v25, v22
	v_and_b32_e32 v22, 0xffff0000, v23
	v_mov_b32_e32 v23, v193
	v_cvt_pk_fp8_f32 v23, v24, v20
	v_lshlrev_b32_e32 v20, 16, v21
	v_and_b32_e32 v21, 0xffff0000, v21
	v_cndmask_b32_e64 v93, v28, 0, vcc
	v_cvt_pk_fp8_f32 v27, v26, v22 op_sel:[0,0,1]
	v_cvt_pk_fp8_f32 v23, v20, v21 op_sel:[0,0,1]
	v_lshlrev_b32_e32 v21, 16, v17
	v_and_b32_e32 v22, 0xffff0000, v17
	v_lshlrev_b32_e32 v17, 16, v18
	v_and_b32_e32 v18, 0xffff0000, v18
	v_mov_b32_e32 v25, v193
	v_cvt_pk_fp8_f32 v25, v17, v18
	v_lshlrev_b32_e32 v20, 16, v16
	v_and_b32_e32 v16, 0xffff0000, v16
	v_mov_b32_e32 v26, v193
	v_cndmask_b32_e64 v94, v94, 0, vcc
	v_lshlrev_b32_e32 v24, 16, v19
	v_cvt_pk_fp8_f32 v26, v20, v16
	v_and_b32_e32 v16, 0xffff0000, v19
	v_cvt_pk_fp8_f32 v25, v24, v16 op_sel:[0,0,1]
	s_waitcnt vmcnt(31)
	v_mfma_f32_16x16x32_fp8_fp8 v[16:19], v[92:93], v[110:111], 0
	v_cndmask_b32_e64 v97, v27, 0, vcc
	v_cvt_pk_fp8_f32 v26, v21, v22 op_sel:[0,0,1]
	v_cndmask_b32_e64 v96, v23, 0, vcc
	v_mfma_f32_16x16x32_fp8_fp8 v[16:19], v[94:95], v[112:113], v[16:19]
	v_cndmask_b32_e64 v99, v25, 0, vcc
	v_cndmask_b32_e64 v98, v26, 0, vcc
	s_waitcnt vmcnt(30)
	v_mfma_f32_16x16x32_fp8_fp8 v[16:19], v[96:97], v[114:115], v[16:19]
	v_cmp_gt_u32_e64 s[4:5], 16, v102
	v_mfma_f32_16x16x32_fp8_fp8 v[16:19], v[98:99], v[116:117], v[16:19]
	s_and_saveexec_b64 s[6:7], s[4:5]
	s_cbranch_execz .LBB0_315
	s_nop 5
	v_mul_f32_e32 v16, 0x3db504f3, v16
	v_cmp_lt_i32_e32 vcc, v90, v105
	v_mul_f32_e32 v17, 0x3db504f3, v17
	s_nop 0
	v_cndmask_b32_e32 v16, v16, v224, vcc
	v_cndmask_b32_e32 v17, v17, v224, vcc
	ds_write2st64_b32 v108, v16, v17 offset1:4
	v_mul_f32_e32 v16, 0x3db504f3, v18
	v_mul_f32_e32 v17, 0x3db504f3, v19
	v_cndmask_b32_e32 v16, v16, v224, vcc
	v_cndmask_b32_e32 v17, v17, v224, vcc
	ds_write2st64_b32 v108, v16, v17 offset0:8 offset1:12
.LBB0_315:
	s_or_b64 exec, exec, s[6:7]
	s_waitcnt vmcnt(29)
	v_mfma_f32_16x16x32_fp8_fp8 v[16:19], v[92:93], v[84:85], 0
	v_mfma_f32_16x16x32_fp8_fp8 v[16:19], v[94:95], v[86:87], v[16:19]
	s_waitcnt vmcnt(28)
	v_mfma_f32_16x16x32_fp8_fp8 v[16:19], v[96:97], v[80:81], v[16:19]
	v_add_u32_e32 v80, 64, v108
	v_mfma_f32_16x16x32_fp8_fp8 v[16:19], v[98:99], v[82:83], v[16:19]
	s_and_saveexec_b64 s[6:7], s[4:5]
	s_cbranch_execz .LBB0_317
	v_or_b32_e32 v28, 16, v105
	v_cmp_gt_i32_e32 vcc, v28, v107
	s_nop 3
	v_mul_f32_e32 v16, 0x3db504f3, v16
	v_mul_f32_e32 v17, 0x3db504f3, v17
	v_cndmask_b32_e32 v16, v16, v224, vcc
	v_cndmask_b32_e32 v17, v17, v224, vcc
	ds_write2st64_b32 v80, v16, v17 offset1:4
	v_mul_f32_e32 v16, 0x3db504f3, v18
	v_mul_f32_e32 v17, 0x3db504f3, v19
	v_cndmask_b32_e32 v16, v16, v224, vcc
	v_cndmask_b32_e32 v17, v17, v224, vcc
	ds_write2st64_b32 v80, v16, v17 offset0:8 offset1:12
.LBB0_317:
	s_or_b64 exec, exec, s[6:7]
	s_waitcnt vmcnt(27)
	v_mfma_f32_16x16x32_fp8_fp8 v[16:19], v[92:93], v[76:77], 0
	v_add_u32_e32 v76, 0x80, v108
	v_mfma_f32_16x16x32_fp8_fp8 v[16:19], v[94:95], v[78:79], v[16:19]
	s_waitcnt vmcnt(26)
	v_mfma_f32_16x16x32_fp8_fp8 v[16:19], v[96:97], v[72:73], v[16:19]
	v_mfma_f32_16x16x32_fp8_fp8 v[16:19], v[98:99], v[74:75], v[16:19]
	s_and_saveexec_b64 s[6:7], s[4:5]
	s_cbranch_execz .LBB0_319
	v_or_b32_e32 v28, 32, v105
	v_cmp_gt_i32_e32 vcc, v28, v107
	s_nop 3
	v_mul_f32_e32 v16, 0x3db504f3, v16
	v_mul_f32_e32 v17, 0x3db504f3, v17
	v_cndmask_b32_e32 v16, v16, v224, vcc
	v_cndmask_b32_e32 v17, v17, v224, vcc
	ds_write2st64_b32 v76, v16, v17 offset1:4
	v_mul_f32_e32 v16, 0x3db504f3, v18
	v_mul_f32_e32 v17, 0x3db504f3, v19
	v_cndmask_b32_e32 v16, v16, v224, vcc
	v_cndmask_b32_e32 v17, v17, v224, vcc
	ds_write2st64_b32 v76, v16, v17 offset0:8 offset1:12
.LBB0_319:
	s_or_b64 exec, exec, s[6:7]
	s_waitcnt vmcnt(25)
	v_mfma_f32_16x16x32_fp8_fp8 v[16:19], v[92:93], v[68:69], 0
	v_add_u32_e32 v77, 0xc0, v108
	v_mfma_f32_16x16x32_fp8_fp8 v[16:19], v[94:95], v[70:71], v[16:19]
	s_waitcnt vmcnt(24)
	v_mfma_f32_16x16x32_fp8_fp8 v[16:19], v[96:97], v[64:65], v[16:19]
	v_mfma_f32_16x16x32_fp8_fp8 v[16:19], v[98:99], v[66:67], v[16:19]
	s_and_saveexec_b64 s[6:7], s[4:5]
	s_cbranch_execz .LBB0_321
	v_or_b32_e32 v28, 48, v105
	v_cmp_gt_i32_e32 vcc, v28, v107
	s_nop 3
	v_mul_f32_e32 v16, 0x3db504f3, v16
	v_mul_f32_e32 v17, 0x3db504f3, v17
	v_cndmask_b32_e32 v16, v16, v224, vcc
	v_cndmask_b32_e32 v17, v17, v224, vcc
	ds_write2st64_b32 v77, v16, v17 offset1:4
	v_mul_f32_e32 v16, 0x3db504f3, v18
	v_mul_f32_e32 v17, 0x3db504f3, v19
	v_cndmask_b32_e32 v16, v16, v224, vcc
	v_cndmask_b32_e32 v17, v17, v224, vcc
	ds_write2st64_b32 v77, v16, v17 offset0:8 offset1:12
.LBB0_321:
	s_or_b64 exec, exec, s[6:7]
	s_waitcnt vmcnt(23)
	v_mfma_f32_16x16x32_fp8_fp8 v[16:19], v[92:93], v[60:61], 0
	v_mfma_f32_16x16x32_fp8_fp8 v[16:19], v[94:95], v[62:63], v[16:19]
	s_waitcnt vmcnt(22)
	v_mfma_f32_16x16x32_fp8_fp8 v[16:19], v[96:97], v[56:57], v[16:19]
	v_mfma_f32_16x16x32_fp8_fp8 v[16:19], v[98:99], v[58:59], v[16:19]
	s_and_saveexec_b64 s[6:7], s[4:5]
	s_cbranch_execz .LBB0_323
	v_or_b32_e32 v28, 64, v105
	v_cmp_gt_i32_e32 vcc, v28, v107
	s_nop 3
	v_mul_f32_e32 v16, 0x3db504f3, v16
	v_mul_f32_e32 v17, 0x3db504f3, v17
	v_cndmask_b32_e32 v16, v16, v224, vcc
	v_cndmask_b32_e32 v17, v17, v224, vcc
	ds_write2st64_b32 v108, v16, v17 offset0:1 offset1:5
	v_mul_f32_e32 v16, 0x3db504f3, v18
	v_mul_f32_e32 v17, 0x3db504f3, v19
	v_cndmask_b32_e32 v16, v16, v224, vcc
	v_cndmask_b32_e32 v17, v17, v224, vcc
	ds_write2st64_b32 v108, v16, v17 offset0:9 offset1:13
; DI void attn_item(const P& p, int b, int kvh, int quad4, char* smem, const AttnPre& pre) {
;     ...
; #pragma unroll
;     for (int u = 0; u < 8; ++u) {
;       const int n = (kt0 + u) * 16 + r;
;       f32x4 acc = {0.f, 0.f, 0.f, 0.f};
; #pragma unroll
;       for (int S = 0; S < 2; ++S) {
;         const long k0 = (long)(((unsigned long long)kraw[u][S][1] << 32) | (unsigned long long)kraw[u][S][0]);
;         const long k1 = (long)(((unsigned long long)kraw[u][S][3] << 32) | (unsigned long long)kraw[u][S][2]);
;         acc = __builtin_amdgcn_mfma_f32_16x16x32_fp8_fp8(qa8[2 * S], k0, acc, 0, 0, 0);
;         acc = __builtin_amdgcn_mfma_f32_16x16x32_fp8_fp8(qa8[2 * S + 1], k1, acc, 0, 0, 0);
;       }
;       if (quad == 0) {
;         const bool ok = n < cnt;
; #pragma unroll
;         for (int h = 0; h < 4; ++h) L[h * 256 + n] = ok ? acc[h] * ATT_SCALE : -INFINITY;
;       }
.LBB0_323:
	s_or_b64 exec, exec, s[6:7]
	s_waitcnt vmcnt(21)
	v_mfma_f32_16x16x32_fp8_fp8 v[16:19], v[92:93], v[52:53], 0
	v_mfma_f32_16x16x32_fp8_fp8 v[16:19], v[94:95], v[54:55], v[16:19]
	s_waitcnt vmcnt(20)
	v_mfma_f32_16x16x32_fp8_fp8 v[16:19], v[96:97], v[48:49], v[16:19]
	v_mfma_f32_16x16x32_fp8_fp8 v[16:19], v[98:99], v[50:51], v[16:19]
	s_and_saveexec_b64 s[6:7], s[4:5]
	s_cbranch_execz .LBB0_325
	v_or_b32_e32 v28, 0x50, v105
	v_cmp_gt_i32_e32 vcc, v28, v107
	s_nop 3
	v_mul_f32_e32 v16, 0x3db504f3, v16
	v_mul_f32_e32 v17, 0x3db504f3, v17
	v_cndmask_b32_e32 v16, v16, v224, vcc
	v_cndmask_b32_e32 v17, v17, v224, vcc
	ds_write2st64_b32 v80, v16, v17 offset0:1 offset1:5
	v_mul_f32_e32 v16, 0x3db504f3, v18
	v_mul_f32_e32 v17, 0x3db504f3, v19
	v_cndmask_b32_e32 v16, v16, v224, vcc
	v_cndmask_b32_e32 v17, v17, v224, vcc
	ds_write2st64_b32 v80, v16, v17 offset0:9 offset1:13
.LBB0_325:
	s_or_b64 exec, exec, s[6:7]
	s_waitcnt vmcnt(19)
	v_mfma_f32_16x16x32_fp8_fp8 v[16:19], v[92:93], v[44:45], 0
	v_mfma_f32_16x16x32_fp8_fp8 v[16:19], v[94:95], v[46:47], v[16:19]
	s_waitcnt vmcnt(18)
	v_mfma_f32_16x16x32_fp8_fp8 v[16:19], v[96:97], v[40:41], v[16:19]
	v_mfma_f32_16x16x32_fp8_fp8 v[16:19], v[98:99], v[42:43], v[16:19]
	s_and_saveexec_b64 s[6:7], s[4:5]
	s_cbranch_execz .LBB0_327
	v_or_b32_e32 v28, 0x60, v105
	v_cmp_gt_i32_e32 vcc, v28, v107
	s_nop 3
	v_mul_f32_e32 v16, 0x3db504f3, v16
	v_mul_f32_e32 v17, 0x3db504f3, v17
	v_cndmask_b32_e32 v16, v16, v224, vcc
	v_cndmask_b32_e32 v17, v17, v224, vcc
	ds_write2st64_b32 v76, v16, v17 offset0:1 offset1:5
	v_mul_f32_e32 v16, 0x3db504f3, v18
	v_mul_f32_e32 v17, 0x3db504f3, v19
	v_cndmask_b32_e32 v16, v16, v224, vcc
	v_cndmask_b32_e32 v17, v17, v224, vcc
	ds_write2st64_b32 v76, v16, v17 offset0:9 offset1:13
.LBB0_327:
	s_or_b64 exec, exec, s[6:7]
	s_waitcnt vmcnt(17)
	v_mfma_f32_16x16x32_fp8_fp8 v[16:19], v[92:93], v[36:37], 0
	v_mfma_f32_16x16x32_fp8_fp8 v[16:19], v[94:95], v[38:39], v[16:19]
	s_waitcnt vmcnt(16)
	v_mfma_f32_16x16x32_fp8_fp8 v[16:19], v[96:97], v[32:33], v[16:19]
	v_mfma_f32_16x16x32_fp8_fp8 v[16:19], v[98:99], v[34:35], v[16:19]
	s_and_saveexec_b64 s[6:7], s[4:5]
	s_cbranch_execz .LBB0_329
	v_or_b32_e32 v28, 0x70, v105
	v_cmp_gt_i32_e32 vcc, v28, v107
	s_nop 3
	v_mul_f32_e32 v16, 0x3db504f3, v16
	v_mul_f32_e32 v17, 0x3db504f3, v17
	v_cndmask_b32_e32 v16, v16, v224, vcc
	v_cndmask_b32_e32 v17, v17, v224, vcc
	ds_write2st64_b32 v77, v16, v17 offset0:1 offset1:5
	v_mul_f32_e32 v16, 0x3db504f3, v18
	v_mul_f32_e32 v17, 0x3db504f3, v19
	v_cndmask_b32_e32 v16, v16, v224, vcc
	v_cndmask_b32_e32 v17, v17, v224, vcc
	ds_write2st64_b32 v77, v16, v17 offset0:9 offset1:13
.LBB0_329:
	s_or_b64 exec, exec, s[6:7]
	s_waitcnt vmcnt(15)
	v_mfma_f32_16x16x32_fp8_fp8 v[20:23], v[92:93], v[120:121], 0
	v_mfma_f32_16x16x32_fp8_fp8 v[16:19], v[94:95], v[122:123], v[20:23]
	s_waitcnt vmcnt(14)
	v_mfma_f32_16x16x32_fp8_fp8 v[82:85], v[96:97], v[124:125], v[16:19]
	s_nop 4
	v_mfma_f32_16x16x32_fp8_fp8 v[72:75], v[98:99], v[126:127], v[82:85]
	s_and_saveexec_b64 s[6:7], s[4:5]
	s_cbranch_execz .LBB0_331
	v_or_b32_e32 v78, 0x80, v105
	v_cmp_gt_i32_e32 vcc, v78, v107
	s_nop 3
	v_mul_f32_e32 v72, 0x3db504f3, v72
	v_mul_f32_e32 v73, 0x3db504f3, v73
	v_cndmask_b32_e32 v72, v72, v224, vcc
	v_cndmask_b32_e32 v73, v73, v224, vcc
	ds_write2st64_b32 v108, v72, v73 offset0:2 offset1:6
	v_mul_f32_e32 v72, 0x3db504f3, v74
	v_mul_f32_e32 v73, 0x3db504f3, v75
	v_cndmask_b32_e32 v72, v72, v224, vcc
	v_cndmask_b32_e32 v73, v73, v224, vcc
	ds_write2st64_b32 v108, v72, v73 offset0:10 offset1:14
.LBB0_331:
	s_or_b64 exec, exec, s[6:7]
	s_waitcnt vmcnt(13)
	v_mfma_f32_16x16x32_fp8_fp8 v[72:75], v[92:93], v[128:129], 0
	v_mfma_f32_16x16x32_fp8_fp8 v[68:71], v[94:95], v[130:131], v[72:75]
	s_waitcnt vmcnt(12)
	v_mfma_f32_16x16x32_fp8_fp8 v[68:71], v[96:97], v[132:133], v[68:71]
	v_mfma_f32_16x16x32_fp8_fp8 v[64:67], v[98:99], v[134:135], v[68:71]
	s_and_saveexec_b64 s[6:7], s[4:5]
	s_cbranch_execz .LBB0_333
	s_nop 4
	v_or_b32_e32 v68, 0x90, v105
	v_cmp_gt_i32_e32 vcc, v68, v107
	v_mul_f32_e32 v64, 0x3db504f3, v64
	v_mul_f32_e32 v65, 0x3db504f3, v65
	v_cndmask_b32_e32 v64, v64, v224, vcc
	v_cndmask_b32_e32 v65, v65, v224, vcc
	ds_write2st64_b32 v80, v64, v65 offset0:2 offset1:6
	v_mul_f32_e32 v64, 0x3db504f3, v66
	v_mul_f32_e32 v65, 0x3db504f3, v67
	v_cndmask_b32_e32 v64, v64, v224, vcc
	v_cndmask_b32_e32 v65, v65, v224, vcc
	ds_write2st64_b32 v80, v64, v65 offset0:10 offset1:14
.LBB0_333:
	s_or_b64 exec, exec, s[6:7]
	s_waitcnt vmcnt(11)
	v_mfma_f32_16x16x32_fp8_fp8 v[64:67], v[92:93], v[136:137], 0
	v_mfma_f32_16x16x32_fp8_fp8 v[60:63], v[94:95], v[138:139], v[64:67]
	s_waitcnt vmcnt(10)
	v_mfma_f32_16x16x32_fp8_fp8 v[60:63], v[96:97], v[140:141], v[60:63]
	v_mfma_f32_16x16x32_fp8_fp8 v[56:59], v[98:99], v[142:143], v[60:63]
	s_and_saveexec_b64 s[6:7], s[4:5]
	s_cbranch_execz .LBB0_335
	s_nop 4
	v_or_b32_e32 v60, 0xa0, v105
	v_cmp_gt_i32_e32 vcc, v60, v107
	v_mul_f32_e32 v56, 0x3db504f3, v56
	v_mul_f32_e32 v57, 0x3db504f3, v57
	v_cndmask_b32_e32 v56, v56, v224, vcc
	v_cndmask_b32_e32 v57, v57, v224, vcc
	ds_write2st64_b32 v76, v56, v57 offset0:2 offset1:6
	v_mul_f32_e32 v56, 0x3db504f3, v58
	v_mul_f32_e32 v57, 0x3db504f3, v59
	v_cndmask_b32_e32 v56, v56, v224, vcc
	v_cndmask_b32_e32 v57, v57, v224, vcc
	ds_write2st64_b32 v76, v56, v57 offset0:10 offset1:14
; DI void attn_item(const P& p, int b, int kvh, int quad4, char* smem, const AttnPre& pre) {
;     ...
; #pragma unroll
;     for (int u = 0; u < 8; ++u) {
;       const int n = (kt0 + u) * 16 + r;
;       f32x4 acc = {0.f, 0.f, 0.f, 0.f};
; #pragma unroll
;       for (int S = 0; S < 2; ++S) {
;         const long k0 = (long)(((unsigned long long)kraw[u][S][1] << 32) | (unsigned long long)kraw[u][S][0]);
;         const long k1 = (long)(((unsigned long long)kraw[u][S][3] << 32) | (unsigned long long)kraw[u][S][2]);
;         acc = __builtin_amdgcn_mfma_f32_16x16x32_fp8_fp8(qa8[2 * S], k0, acc, 0, 0, 0);
;         acc = __builtin_amdgcn_mfma_f32_16x16x32_fp8_fp8(qa8[2 * S + 1], k1, acc, 0, 0, 0);
;       }
;       if (quad == 0) {
;         const bool ok = n < cnt;
; #pragma unroll
;         for (int h = 0; h < 4; ++h) L[h * 256 + n] = ok ? acc[h] * ATT_SCALE : -INFINITY;
;       }
.LBB0_335:
	s_or_b64 exec, exec, s[6:7]
	s_waitcnt vmcnt(9)
	v_mfma_f32_16x16x32_fp8_fp8 v[56:59], v[92:93], v[144:145], 0
	v_mfma_f32_16x16x32_fp8_fp8 v[52:55], v[94:95], v[146:147], v[56:59]
	s_waitcnt vmcnt(8)
	v_mfma_f32_16x16x32_fp8_fp8 v[52:55], v[96:97], v[148:149], v[52:55]
	v_mfma_f32_16x16x32_fp8_fp8 v[48:51], v[98:99], v[150:151], v[52:55]
	s_and_saveexec_b64 s[6:7], s[4:5]
	s_cbranch_execz .LBB0_337
	s_nop 4
	v_or_b32_e32 v52, 0xb0, v105
	v_cmp_gt_i32_e32 vcc, v52, v107
	v_mul_f32_e32 v48, 0x3db504f3, v48
	v_mul_f32_e32 v49, 0x3db504f3, v49
	v_cndmask_b32_e32 v48, v48, v224, vcc
	v_cndmask_b32_e32 v49, v49, v224, vcc
	ds_write2st64_b32 v77, v48, v49 offset0:2 offset1:6
	v_mul_f32_e32 v48, 0x3db504f3, v50
	v_mul_f32_e32 v49, 0x3db504f3, v51
	v_cndmask_b32_e32 v48, v48, v224, vcc
	v_cndmask_b32_e32 v49, v49, v224, vcc
	ds_write2st64_b32 v77, v48, v49 offset0:10 offset1:14
.LBB0_337:
	s_or_b64 exec, exec, s[6:7]
	s_waitcnt vmcnt(7)
	v_mfma_f32_16x16x32_fp8_fp8 v[48:51], v[92:93], v[152:153], 0
	v_mfma_f32_16x16x32_fp8_fp8 v[44:47], v[94:95], v[154:155], v[48:51]
	s_waitcnt vmcnt(6)
	v_mfma_f32_16x16x32_fp8_fp8 v[44:47], v[96:97], v[156:157], v[44:47]
	v_mfma_f32_16x16x32_fp8_fp8 v[40:43], v[98:99], v[158:159], v[44:47]
	s_and_saveexec_b64 s[6:7], s[4:5]
	s_cbranch_execz .LBB0_339
	s_nop 4
	v_or_b32_e32 v44, 0xc0, v105
	v_cmp_gt_i32_e32 vcc, v44, v107
	v_mul_f32_e32 v40, 0x3db504f3, v40
	v_mul_f32_e32 v41, 0x3db504f3, v41
	v_cndmask_b32_e32 v40, v40, v224, vcc
	v_cndmask_b32_e32 v41, v41, v224, vcc
	ds_write2st64_b32 v108, v40, v41 offset0:3 offset1:7
	v_mul_f32_e32 v40, 0x3db504f3, v42
	v_mul_f32_e32 v41, 0x3db504f3, v43
	v_cndmask_b32_e32 v40, v40, v224, vcc
	v_cndmask_b32_e32 v41, v41, v224, vcc
	ds_write2st64_b32 v108, v40, v41 offset0:11 offset1:15
.LBB0_339:
	s_or_b64 exec, exec, s[6:7]
	s_waitcnt vmcnt(5)
	v_mfma_f32_16x16x32_fp8_fp8 v[40:43], v[92:93], v[160:161], 0
	v_mfma_f32_16x16x32_fp8_fp8 v[36:39], v[94:95], v[162:163], v[40:43]
	s_waitcnt vmcnt(4)
	v_mfma_f32_16x16x32_fp8_fp8 v[36:39], v[96:97], v[164:165], v[36:39]
	v_mfma_f32_16x16x32_fp8_fp8 v[32:35], v[98:99], v[166:167], v[36:39]
	s_and_saveexec_b64 s[6:7], s[4:5]
	s_cbranch_execz .LBB0_341
	s_nop 4
	v_or_b32_e32 v36, 0xd0, v105
	v_cmp_gt_i32_e32 vcc, v36, v107
	v_mul_f32_e32 v32, 0x3db504f3, v32
	v_mul_f32_e32 v33, 0x3db504f3, v33
	v_cndmask_b32_e32 v32, v32, v224, vcc
	v_cndmask_b32_e32 v33, v33, v224, vcc
	ds_write2st64_b32 v80, v32, v33 offset0:3 offset1:7
	v_mul_f32_e32 v32, 0x3db504f3, v34
	v_mul_f32_e32 v33, 0x3db504f3, v35
	v_cndmask_b32_e32 v32, v32, v224, vcc
	v_cndmask_b32_e32 v33, v33, v224, vcc
	ds_write2st64_b32 v80, v32, v33 offset0:11 offset1:15
.LBB0_341:
	s_or_b64 exec, exec, s[6:7]
	s_waitcnt vmcnt(3)
	v_mfma_f32_16x16x32_fp8_fp8 v[32:35], v[92:93], v[196:197], 0
	v_mfma_f32_16x16x32_fp8_fp8 v[28:31], v[94:95], v[198:199], v[32:35]
	s_waitcnt vmcnt(2)
	v_mfma_f32_16x16x32_fp8_fp8 v[28:31], v[96:97], v[200:201], v[28:31]
	v_mfma_f32_16x16x32_fp8_fp8 v[24:27], v[98:99], v[202:203], v[28:31]
	s_and_saveexec_b64 s[6:7], s[4:5]
	s_cbranch_execz .LBB0_343
	s_nop 4
	v_or_b32_e32 v28, 0xe0, v105
	v_cmp_gt_i32_e32 vcc, v28, v107
	v_mul_f32_e32 v24, 0x3db504f3, v24
	v_mul_f32_e32 v25, 0x3db504f3, v25
	v_cndmask_b32_e32 v24, v24, v224, vcc
	v_cndmask_b32_e32 v25, v25, v224, vcc
	ds_write2st64_b32 v76, v24, v25 offset0:3 offset1:7
	v_mul_f32_e32 v24, 0x3db504f3, v26
	v_mul_f32_e32 v25, 0x3db504f3, v27
	v_cndmask_b32_e32 v24, v24, v224, vcc
	v_cndmask_b32_e32 v25, v25, v224, vcc
	ds_write2st64_b32 v76, v24, v25 offset0:11 offset1:15
.LBB0_343:
	s_or_b64 exec, exec, s[6:7]
	s_waitcnt vmcnt(1)
	v_mfma_f32_16x16x32_fp8_fp8 v[24:27], v[92:93], v[204:205], 0
	v_mfma_f32_16x16x32_fp8_fp8 v[20:23], v[94:95], v[206:207], v[24:27]
	s_waitcnt vmcnt(0)
	v_mfma_f32_16x16x32_fp8_fp8 v[20:23], v[96:97], v[208:209], v[20:23]
	v_mfma_f32_16x16x32_fp8_fp8 v[16:19], v[98:99], v[210:211], v[20:23]
	s_and_saveexec_b64 s[6:7], s[4:5]
	s_cbranch_execz .LBB0_345
	s_nop 4
	v_or_b32_e32 v20, 0xf0, v105
	v_cmp_gt_i32_e32 vcc, v20, v107
	v_mul_f32_e32 v16, 0x3db504f3, v16
	v_mul_f32_e32 v17, 0x3db504f3, v17
	v_cndmask_b32_e32 v16, v16, v224, vcc
	v_cndmask_b32_e32 v17, v17, v224, vcc
	ds_write2st64_b32 v77, v16, v17 offset0:3 offset1:7
	v_mul_f32_e32 v16, 0x3db504f3, v18
	v_mul_f32_e32 v17, 0x3db504f3, v19
	v_cndmask_b32_e32 v16, v16, v224, vcc
	v_cndmask_b32_e32 v17, v17, v224, vcc
	ds_write2st64_b32 v77, v16, v17 offset0:11 offset1:15
